# v38 + MLA row sums as a running v_pk_add_f32 pair (16 instead of 34 adds per wave-iteration), 32-bit address steps
# speedup vs baseline: 1.0018x; 1.0018x over previous
.LBB0_376:
	s_max_i32 s20, s34, 1
	s_cmp_eq_u32 s20, 1
	s_waitcnt lgkmcnt(0)
	s_barrier
	s_cbranch_scc1 .LBB0_359
	v_lshlrev_b64 v[4:5], 7, v[86:87]
	v_and_b32_e32 v2, 7, v98
	v_lshl_add_u64 v[4:5], s[10:11], 0, v[4:5]
	v_lshlrev_b32_e32 v2, 4, v2
	v_lshl_add_u64 v[4:5], v[4:5], 0, v[2:3]
	v_lshlrev_b64 v[6:7], 11, v[84:85]
	v_and_b32_e32 v2, 15, v98
	v_lshl_add_u64 v[6:7], s[12:13], 0, v[6:7]
	v_lshlrev_b32_e32 v2, 4, v2
	s_or_b32 s36, s33, 2
	v_add_u32_e32 v19, v188, v99
	v_lshl_add_u64 v[6:7], v[6:7], 0, v[2:3]
	s_mov_b32 s37, -3
	v_xor_b32_e32 v210, 0x80000000, v192
	v_mov_b32_e32 v211, v210
	v_mov_b32_e32 v212, v210
	v_mov_b32_e32 v213, v210
	v_mov_b32_e32 v214, v210
	v_mov_b32_e32 v215, v210
	v_mov_b32_e32 v216, v210
	v_mov_b32_e32 v217, v210
	v_mov_b32_e32 v218, v210
	v_mov_b32_e32 v219, v210
	v_mov_b32_e32 v220, v210
	v_mov_b32_e32 v221, v210
	v_mov_b32_e32 v222, v210
	v_mov_b32_e32 v223, v210
	v_mov_b32_e32 v224, v210
	v_mov_b32_e32 v225, v210
	v_mov_b32_e32 v240, v193
	v_mov_b32_e32 v241, 0
	s_branch .LBB0_380

.Lm_nowrite:
	s_add_i32 s20, s37, 4
	s_cmp_ge_i32 s20, s36
	s_cbranch_scc1 .Lm_noload
	v_add_u32_e32 v242, 0x10000, v6
	v_add_u32_e32 v243, 0x4000000, v6
	v_add_u32_e32 v234, 0x4010000, v6
	global_load_dwordx4 v[128:131], v6, s[98:99]
	global_load_dwordx4 v[168:171], v242, s[98:99]
	global_load_dwordx4 v[172:175], v243, s[98:99]
	global_load_dwordx4 v[180:183], v234, s[98:99]
	global_load_dwordx4 v[176:179], v4, s[100:101]

.Lm_cont:
	v_exp_f32_e32 v100, v100
	v_exp_f32_e32 v101, v101
	v_exp_f32_e32 v102, v102
	v_exp_f32_e32 v103, v103
	v_exp_f32_e32 v104, v104
	v_exp_f32_e32 v105, v105
	v_exp_f32_e32 v106, v106
	v_exp_f32_e32 v107, v107
	v_pk_add_f32 v[240:241], v[240:241], v[100:101]
	v_pk_add_f32 v[240:241], v[240:241], v[102:103]
	v_pk_add_f32 v[240:241], v[240:241], v[104:105]
	v_pk_add_f32 v[240:241], v[240:241], v[106:107]
	v_cvt_pk_bf16_f32 v226, v100, v101
	v_cvt_pk_bf16_f32 v227, v102, v103
	v_cvt_pk_bf16_f32 v228, v104, v105
	v_cvt_pk_bf16_f32 v229, v106, v107
	s_waitcnt lgkmcnt(6)
	s_nop 0
	v_mfma_f32_32x32x16_bf16 v[68:83], v[10:13], v[226:229], v[68:83]
	v_exp_f32_e32 v108, v108
	v_exp_f32_e32 v109, v109
	v_exp_f32_e32 v110, v110
	v_exp_f32_e32 v111, v111
	s_waitcnt lgkmcnt(4)
	v_mfma_f32_32x32x16_bf16 v[52:67], v[14:17], v[226:229], v[52:67]
	v_exp_f32_e32 v112, v112
	v_exp_f32_e32 v113, v113
	v_exp_f32_e32 v114, v114
	v_exp_f32_e32 v115, v115
	s_waitcnt lgkmcnt(2)
	v_mfma_f32_32x32x16_bf16 v[36:51], v[202:205], v[226:229], v[36:51]
	v_pk_add_f32 v[240:241], v[240:241], v[108:109]
	v_pk_add_f32 v[240:241], v[240:241], v[110:111]
	s_waitcnt lgkmcnt(0)
	v_mfma_f32_32x32x16_bf16 v[20:35], v[206:209], v[226:229], v[20:35]
	v_pk_add_f32 v[240:241], v[240:241], v[112:113]
	v_pk_add_f32 v[240:241], v[240:241], v[114:115]
	v_cvt_pk_bf16_f32 v230, v108, v109
	v_cvt_pk_bf16_f32 v231, v110, v111
	v_cvt_pk_bf16_f32 v232, v112, v113
	v_cvt_pk_bf16_f32 v233, v114, v115
	ds_read_b64_tr_b16 v[100:101], v197 offset:30720
	ds_read_b64_tr_b16 v[102:103], v197 offset:33280
	ds_read_b64_tr_b16 v[104:105], v197 offset:30784
	ds_read_b64_tr_b16 v[106:107], v197 offset:33344
	ds_read_b64_tr_b16 v[108:109], v197 offset:30848
	ds_read_b64_tr_b16 v[110:111], v197 offset:33408
	ds_read_b64_tr_b16 v[112:113], v197 offset:30912
	ds_read_b64_tr_b16 v[114:115], v197 offset:33472
	ds_read_b64_tr_b16 v[10:11], v197 offset:35840
	ds_read_b64_tr_b16 v[12:13], v197 offset:38400
	ds_read_b64_tr_b16 v[14:15], v197 offset:35904
	ds_read_b64_tr_b16 v[16:17], v197 offset:38464
	ds_read_b64_tr_b16 v[202:203], v197 offset:35968
	ds_read_b64_tr_b16 v[204:205], v197 offset:38528
	ds_read_b64_tr_b16 v[206:207], v197 offset:36032
	ds_read_b64_tr_b16 v[208:209], v197 offset:38592
	v_exp_f32_e32 v84, v84
	v_exp_f32_e32 v85, v85
	v_exp_f32_e32 v86, v86
	v_exp_f32_e32 v87, v87
	v_exp_f32_e32 v88, v88
	v_exp_f32_e32 v89, v89
	v_exp_f32_e32 v90, v90
	v_exp_f32_e32 v91, v91
	v_pk_add_f32 v[240:241], v[240:241], v[84:85]
	v_pk_add_f32 v[240:241], v[240:241], v[86:87]
	v_pk_add_f32 v[240:241], v[240:241], v[88:89]
	v_pk_add_f32 v[240:241], v[240:241], v[90:91]
	v_cvt_pk_bf16_f32 v226, v84, v85
	v_cvt_pk_bf16_f32 v227, v86, v87
	v_cvt_pk_bf16_f32 v228, v88, v89
	v_cvt_pk_bf16_f32 v229, v90, v91
	s_waitcnt lgkmcnt(14)
	v_mfma_f32_32x32x16_bf16 v[68:83], v[100:103], v[230:233], v[68:83]
	v_exp_f32_e32 v92, v92
	v_exp_f32_e32 v93, v93
	v_exp_f32_e32 v94, v94
	v_exp_f32_e32 v95, v95
	s_waitcnt lgkmcnt(12)
	v_mfma_f32_32x32x16_bf16 v[52:67], v[104:107], v[230:233], v[52:67]
	v_exp_f32_e32 v96, v96
	v_exp_f32_e32 v97, v97
	v_exp_f32_e32 v98, v98
	v_exp_f32_e32 v99, v99
	s_waitcnt lgkmcnt(10)
	v_mfma_f32_32x32x16_bf16 v[36:51], v[108:111], v[230:233], v[36:51]
	v_pk_add_f32 v[240:241], v[240:241], v[92:93]
	v_pk_add_f32 v[240:241], v[240:241], v[94:95]
	s_waitcnt lgkmcnt(8)
	v_mfma_f32_32x32x16_bf16 v[20:35], v[112:115], v[230:233], v[20:35]
	ds_read_b64_tr_b16 v[100:101], v197 offset:40960
	ds_read_b64_tr_b16 v[102:103], v197 offset:43520
	ds_read_b64_tr_b16 v[104:105], v197 offset:41024
	ds_read_b64_tr_b16 v[106:107], v197 offset:43584
	ds_read_b64_tr_b16 v[108:109], v197 offset:41088
	ds_read_b64_tr_b16 v[110:111], v197 offset:43648
	ds_read_b64_tr_b16 v[112:113], v197 offset:41152
	ds_read_b64_tr_b16 v[114:115], v197 offset:43712
	v_pk_add_f32 v[240:241], v[240:241], v[96:97]
	v_pk_add_f32 v[240:241], v[240:241], v[98:99]
	v_cvt_pk_bf16_f32 v230, v92, v93
	v_cvt_pk_bf16_f32 v231, v94, v95
	v_cvt_pk_bf16_f32 v232, v96, v97
	v_cvt_pk_bf16_f32 v233, v98, v99
	s_waitcnt lgkmcnt(14)
	v_mfma_f32_32x32x16_bf16 v[68:83], v[10:13], v[226:229], v[68:83]
	s_waitcnt lgkmcnt(12)
	v_mfma_f32_32x32x16_bf16 v[52:67], v[14:17], v[226:229], v[52:67]
	s_waitcnt lgkmcnt(10)
	v_mfma_f32_32x32x16_bf16 v[36:51], v[202:205], v[226:229], v[36:51]
	s_waitcnt lgkmcnt(8)
	v_mfma_f32_32x32x16_bf16 v[20:35], v[206:209], v[226:229], v[20:35]
	s_waitcnt lgkmcnt(6)
	v_mfma_f32_32x32x16_bf16 v[68:83], v[100:103], v[230:233], v[68:83]
	s_waitcnt lgkmcnt(4)
	v_mfma_f32_32x32x16_bf16 v[52:67], v[104:107], v[230:233], v[52:67]
	s_waitcnt lgkmcnt(2)
	v_mfma_f32_32x32x16_bf16 v[36:51], v[108:111], v[230:233], v[36:51]
	s_waitcnt lgkmcnt(0)
	v_mfma_f32_32x32x16_bf16 v[20:35], v[112:115], v[230:233], v[20:35]
.LBB0_379:
	s_add_i32 s37, s37, 1
	v_add_u32_e32 v4, s14, v4
	s_cmp_lg_u32 s33, s37
	v_add_u32_e32 v6, s16, v6
	s_waitcnt lgkmcnt(0)
	s_barrier
	s_cbranch_scc1 .LBB0_380
	v_add_f32_e32 v193, v240, v241
	s_branch .LBB0_359
.Lm_R:
	v_max_f32_e32 v236, v236, v236
	v_max_f32_e32 v236, 0, v236
	v_exp_f32_e64 v238, -v236
	v_pk_add_f32 v[100:101], v[100:101], v[236:237] op_sel_hi:[1,0] neg_lo:[0,1] neg_hi:[0,1]
	v_pk_add_f32 v[102:103], v[102:103], v[236:237] op_sel_hi:[1,0] neg_lo:[0,1] neg_hi:[0,1]
	v_pk_add_f32 v[104:105], v[104:105], v[236:237] op_sel_hi:[1,0] neg_lo:[0,1] neg_hi:[0,1]
	v_pk_add_f32 v[106:107], v[106:107], v[236:237] op_sel_hi:[1,0] neg_lo:[0,1] neg_hi:[0,1]
	v_pk_add_f32 v[108:109], v[108:109], v[236:237] op_sel_hi:[1,0] neg_lo:[0,1] neg_hi:[0,1]
	v_pk_add_f32 v[110:111], v[110:111], v[236:237] op_sel_hi:[1,0] neg_lo:[0,1] neg_hi:[0,1]
	v_pk_add_f32 v[112:113], v[112:113], v[236:237] op_sel_hi:[1,0] neg_lo:[0,1] neg_hi:[0,1]
	v_pk_add_f32 v[114:115], v[114:115], v[236:237] op_sel_hi:[1,0] neg_lo:[0,1] neg_hi:[0,1]
	v_pk_add_f32 v[84:85], v[84:85], v[236:237] op_sel_hi:[1,0] neg_lo:[0,1] neg_hi:[0,1]
	v_pk_add_f32 v[86:87], v[86:87], v[236:237] op_sel_hi:[1,0] neg_lo:[0,1] neg_hi:[0,1]
	v_pk_add_f32 v[88:89], v[88:89], v[236:237] op_sel_hi:[1,0] neg_lo:[0,1] neg_hi:[0,1]
	v_pk_add_f32 v[90:91], v[90:91], v[236:237] op_sel_hi:[1,0] neg_lo:[0,1] neg_hi:[0,1]
	v_pk_add_f32 v[92:93], v[92:93], v[236:237] op_sel_hi:[1,0] neg_lo:[0,1] neg_hi:[0,1]
	v_pk_add_f32 v[94:95], v[94:95], v[236:237] op_sel_hi:[1,0] neg_lo:[0,1] neg_hi:[0,1]
	v_pk_add_f32 v[96:97], v[96:97], v[236:237] op_sel_hi:[1,0] neg_lo:[0,1] neg_hi:[0,1]
	v_pk_add_f32 v[98:99], v[98:99], v[236:237] op_sel_hi:[1,0] neg_lo:[0,1] neg_hi:[0,1]
	v_pk_add_f32 v[210:211], v[210:211], v[236:237] op_sel_hi:[1,0] neg_lo:[0,1] neg_hi:[0,1]
	v_pk_add_f32 v[212:213], v[212:213], v[236:237] op_sel_hi:[1,0] neg_lo:[0,1] neg_hi:[0,1]
	v_pk_add_f32 v[214:215], v[214:215], v[236:237] op_sel_hi:[1,0] neg_lo:[0,1] neg_hi:[0,1]
	v_pk_add_f32 v[216:217], v[216:217], v[236:237] op_sel_hi:[1,0] neg_lo:[0,1] neg_hi:[0,1]
	v_pk_add_f32 v[218:219], v[218:219], v[236:237] op_sel_hi:[1,0] neg_lo:[0,1] neg_hi:[0,1]
	v_pk_add_f32 v[220:221], v[220:221], v[236:237] op_sel_hi:[1,0] neg_lo:[0,1] neg_hi:[0,1]
	v_pk_add_f32 v[222:223], v[222:223], v[236:237] op_sel_hi:[1,0] neg_lo:[0,1] neg_hi:[0,1]
	v_pk_add_f32 v[224:225], v[224:225], v[236:237] op_sel_hi:[1,0] neg_lo:[0,1] neg_hi:[0,1]
	v_pk_mul_f32 v[240:241], v[240:241], v[238:239] op_sel_hi:[1,0]
	v_pk_mul_f32 v[68:69], v[68:69], v[238:239] op_sel_hi:[1,0]
	v_pk_mul_f32 v[70:71], v[70:71], v[238:239] op_sel_hi:[1,0]
	v_pk_mul_f32 v[72:73], v[72:73], v[238:239] op_sel_hi:[1,0]
	v_pk_mul_f32 v[74:75], v[74:75], v[238:239] op_sel_hi:[1,0]
	v_pk_mul_f32 v[76:77], v[76:77], v[238:239] op_sel_hi:[1,0]
	v_pk_mul_f32 v[78:79], v[78:79], v[238:239] op_sel_hi:[1,0]
	v_pk_mul_f32 v[80:81], v[80:81], v[238:239] op_sel_hi:[1,0]
	v_pk_mul_f32 v[82:83], v[82:83], v[238:239] op_sel_hi:[1,0]
	v_pk_mul_f32 v[52:53], v[52:53], v[238:239] op_sel_hi:[1,0]
	v_pk_mul_f32 v[54:55], v[54:55], v[238:239] op_sel_hi:[1,0]
	v_pk_mul_f32 v[56:57], v[56:57], v[238:239] op_sel_hi:[1,0]
	v_pk_mul_f32 v[58:59], v[58:59], v[238:239] op_sel_hi:[1,0]
	v_pk_mul_f32 v[60:61], v[60:61], v[238:239] op_sel_hi:[1,0]
	v_pk_mul_f32 v[62:63], v[62:63], v[238:239] op_sel_hi:[1,0]
	v_pk_mul_f32 v[64:65], v[64:65], v[238:239] op_sel_hi:[1,0]
	v_pk_mul_f32 v[66:67], v[66:67], v[238:239] op_sel_hi:[1,0]
	v_pk_mul_f32 v[36:37], v[36:37], v[238:239] op_sel_hi:[1,0]
	v_pk_mul_f32 v[38:39], v[38:39], v[238:239] op_sel_hi:[1,0]
	v_pk_mul_f32 v[40:41], v[40:41], v[238:239] op_sel_hi:[1,0]
	v_pk_mul_f32 v[42:43], v[42:43], v[238:239] op_sel_hi:[1,0]
	v_pk_mul_f32 v[44:45], v[44:45], v[238:239] op_sel_hi:[1,0]
	v_pk_mul_f32 v[46:47], v[46:47], v[238:239] op_sel_hi:[1,0]
	v_pk_mul_f32 v[48:49], v[48:49], v[238:239] op_sel_hi:[1,0]
	v_pk_mul_f32 v[50:51], v[50:51], v[238:239] op_sel_hi:[1,0]
	v_pk_mul_f32 v[20:21], v[20:21], v[238:239] op_sel_hi:[1,0]
	v_pk_mul_f32 v[22:23], v[22:23], v[238:239] op_sel_hi:[1,0]
	v_pk_mul_f32 v[24:25], v[24:25], v[238:239] op_sel_hi:[1,0]
	v_pk_mul_f32 v[26:27], v[26:27], v[238:239] op_sel_hi:[1,0]
	v_pk_mul_f32 v[28:29], v[28:29], v[238:239] op_sel_hi:[1,0]
	v_pk_mul_f32 v[30:31], v[30:31], v[238:239] op_sel_hi:[1,0]
	v_pk_mul_f32 v[32:33], v[32:33], v[238:239] op_sel_hi:[1,0]
	v_pk_mul_f32 v[34:35], v[34:35], v[238:239] op_sel_hi:[1,0]
	v_add_f32_e32 v192, v192, v236
	s_branch .Lm_cont
